# prologue x-row loop, p conversion loops and final-norm loop: loads batched and next row prefetched (was one load per wait)
# speedup vs baseline: 1.0553x; 1.0147x over previous
; __device__ __forceinline__ unsigned pk2(float lo, float hi) { f32x2 v = {lo, hi}; bf16x2_t b = __builtin_convertvector(v, bf16x2_t); return __builtin_bit_cast(unsigned, b); }
; __device__ __forceinline__ float sumsq4(const f32x4 v) { return (v[0] * v[0] + v[1] * v[1]) + (v[2] * v[2] + v[3] * v[3]); }
; __global__ void __launch_bounds__(512, 2) hybrid_fwd(Args args) {
;     ...
;                 for (int m = gw; m < M; m += NGW) {
;                     const f32x4* xr = (const f32x4*)(args.in[0 + z_] + (size_t)m * D) + lane;
;                     u32x2* br = (u32x2*)(HBALT + (size_t)m * D) + lane;
;                     float s = 0.f;
; #pragma unroll
;                     for (int j = 0; j < 4; ++j) { const f32x4 v = __builtin_nontemporal_load(xr + 64 * j); s += sumsq4(v); u32x2 w; w.x = pk2(v[0], v[1]); w.y = pk2(v[2], v[3]); br[64 * j] = w; }
;                     s = wave_sum(s);
;                     if (lane == 0) ss0[m] = (ssq_t)(s * 1048576.0f + 0.5f);
;                 }
.LBB0_14:
	s_and_b64 vcc, exec, s[14:15]
	s_cbranch_vccnz .LBB0_357
	v_readlane_b32 s2, v255, 28
	v_mov_b32_e32 v38, v194
	v_readlane_b32 s3, v255, 29
	s_mov_b64 s[6:7], 0
	v_and_b32_e32 v10, 63, v38
	s_andn2_b64 vcc, exec, s[2:3]
	s_cbranch_vccnz .LBB0_28
	v_readlane_b32 s2, v252, 19
	v_readlane_b32 s3, v252, 20
	s_andn2_b64 vcc, exec, s[2:3]
	s_cbranch_vccnz .LBB0_21
	s_lshl_b64 s[2:3], s[6:7], 3
	v_readlane_b32 s8, v252, 0
	v_readlane_b32 s9, v252, 1
	s_add_u32 s2, s8, s2
	s_addc_u32 s3, s9, s3
	s_load_dwordx2 s[8:9], s[2:3], 0x0
	v_readlane_b32 s1, v254, 8
	s_add_u32 s2, s1, s6
	v_readlane_b32 s1, v254, 9
	s_addc_u32 s3, s1, s7
	v_readlane_b32 s1, v254, 10
	s_waitcnt lgkmcnt(0)
	s_add_u32 s8, s8, s1
	v_readlane_b32 s1, v254, 54
	v_lshlrev_b32_e32 v98, 4, v10
	s_addc_u32 s9, s9, s1
	v_readlane_b32 s1, v254, 19
	v_lshl_add_u64 v[2:3], s[8:9], 0, v[98:99]
	s_add_u32 s8, s1, s6
	v_readlane_b32 s1, v254, 20
	v_lshlrev_b32_e32 v98, 3, v10
	s_addc_u32 s9, s1, s7
	v_lshl_add_u64 v[4:5], s[8:9], 0, v[98:99]
	v_readlane_b32 s8, v254, 15
	v_cmp_eq_u32_e32 vcc, 0, v10
	s_mov_b32 s4, s8
	v_readlane_b32 s9, v254, 16
	global_load_dwordx4 v[6:9], v[2:3], off offset:-3072 nt
	global_load_dwordx4 v[12:15], v[2:3], off offset:-2048 nt
	global_load_dwordx4 v[16:19], v[2:3], off offset:-1024 nt
	global_load_dwordx4 v[20:23], v[2:3], off nt
	s_branch .LBB0_19
.LBB0_18:
	s_or_b64 exec, exec, s[8:9]
	s_add_i32 s4, s4, s80
	v_readlane_b32 s8, v254, 11
	v_readlane_b32 s9, v254, 12
	s_add_u32 s2, s2, s8
	s_addc_u32 s3, s3, s9
	s_cmpk_gt_i32 s4, 0x3fff
	v_readlane_b32 s8, v254, 21
	v_readlane_b32 s9, v254, 22
	s_nop 1
	v_lshl_add_u64 v[4:5], v[4:5], 0, s[8:9]
	s_cbranch_scc1 .LBB0_21
.LBB0_19:
	s_waitcnt vmcnt(0)
	v_cvt_pk_bf16_f32 v24, v6, v7
	v_cvt_pk_bf16_f32 v25, v8, v9
	v_mul_f32_e32 v1, v7, v7
	v_mul_f32_e32 v7, v9, v9
	v_fmac_f32_e32 v1, v6, v6
	v_fmac_f32_e32 v7, v8, v8
	v_add_f32_e32 v1, v1, v7
	v_cvt_pk_bf16_f32 v26, v12, v13
	v_cvt_pk_bf16_f32 v27, v14, v15
	v_mul_f32_e32 v6, v13, v13
	v_mul_f32_e32 v7, v15, v15
	v_fmac_f32_e32 v6, v12, v12
	v_fmac_f32_e32 v7, v14, v14
	v_add_f32_e32 v6, v6, v7
	v_add_f32_e32 v1, v1, v6
	v_cvt_pk_bf16_f32 v28, v16, v17
	v_cvt_pk_bf16_f32 v29, v18, v19
	v_mul_f32_e32 v6, v17, v17
	v_mul_f32_e32 v7, v19, v19
	v_fmac_f32_e32 v6, v16, v16
	v_fmac_f32_e32 v7, v18, v18
	v_add_f32_e32 v6, v6, v7
	v_add_f32_e32 v1, v1, v6
	v_cvt_pk_bf16_f32 v30, v20, v21
	v_cvt_pk_bf16_f32 v31, v22, v23
	v_mul_f32_e32 v6, v21, v21
	v_mul_f32_e32 v7, v23, v23
	v_fmac_f32_e32 v6, v20, v20
	v_fmac_f32_e32 v7, v22, v22
	v_add_f32_e32 v6, v6, v7
	v_add_f32_e32 v1, v1, v6
	global_store_dwordx2 v[4:5], v[24:25], off offset:-1024
	global_store_dwordx2 v[4:5], v[26:27], off offset:-512
	global_store_dwordx2 v[4:5], v[28:29], off
	global_store_dwordx2 v[4:5], v[30:31], off offset:512
	v_readlane_b32 s8, v254, 13
	v_readlane_b32 s9, v254, 14
	s_add_i32 s1, s4, s80
	s_nop 0
	v_lshl_add_u64 v[2:3], v[2:3], 0, s[8:9]
	s_cmpk_gt_i32 s1, 0x3fff
	s_cbranch_scc1 .Lxrow_last
	global_load_dwordx4 v[6:9], v[2:3], off offset:-3072 nt
	global_load_dwordx4 v[12:15], v[2:3], off offset:-2048 nt
	global_load_dwordx4 v[16:19], v[2:3], off offset:-1024 nt
	global_load_dwordx4 v[20:23], v[2:3], off nt
.Lxrow_last:
	ds_swizzle_b32 v32, v1 offset:swizzle(SWAP,1)
	s_waitcnt lgkmcnt(0)
	v_add_f32_e32 v1, v1, v32
	ds_swizzle_b32 v32, v1 offset:swizzle(SWAP,2)
	s_waitcnt lgkmcnt(0)
	v_add_f32_e32 v1, v1, v32
	ds_swizzle_b32 v32, v1 offset:swizzle(SWAP,4)
	s_waitcnt lgkmcnt(0)
	v_add_f32_e32 v1, v1, v32
	ds_swizzle_b32 v32, v1 offset:swizzle(SWAP,8)
	s_waitcnt lgkmcnt(0)
	v_add_f32_e32 v1, v1, v32
	ds_swizzle_b32 v34, v1 offset:swizzle(SWAP,16)
	s_waitcnt lgkmcnt(0)
	v_add_f32_e32 v1, v1, v34
	v_mov_b32_e32 v32, v1
	s_nop 1
	v_permlane32_swap_b32_e32 v1, v32
	s_and_saveexec_b64 s[8:9], vcc
	s_cbranch_execz .LBB0_18
	v_add_f32_e32 v1, v1, v32
	s_mov_b32 s1, 0x49800000
	v_fma_f32 v1, v1, s1, 0.5
	v_trunc_f32_e32 v1, v1
	v_mul_f32_e32 v32, 0x2f800000, v1
	v_floor_f32_e32 v33, v32
	v_fmac_f32_e32 v1, 0xcf800000, v33
	v_cvt_u32_f32_e32 v32, v1
	v_cvt_u32_f32_e32 v33, v33
	global_store_dwordx2 v99, v[32:33], s[2:3]
	s_branch .LBB0_18

.Lconvp8_a:
	v_lshl_add_u64 v[12:13], v[2:3], 0, s[16:17]
	v_lshl_add_u64 v[12:13], v[12:13], 0, s[16:17]
	v_lshl_add_u64 v[12:13], v[12:13], 0, s[16:17]
	v_lshl_add_u64 v[12:13], v[12:13], 0, s[16:17]
	v_lshl_add_u64 v[12:13], v[12:13], 0, s[16:17]
	v_lshl_add_u64 v[12:13], v[12:13], 0, s[16:17]
	v_lshl_add_u64 v[12:13], v[12:13], 0, s[16:17]
	v_cmp_lt_u64_e32 vcc, s[40:41], v[12:13]
	s_cbranch_vccnz .LBB0_355
	global_load_dwordx4 v[14:17], v[4:5], off nt
	v_lshl_add_u64 v[4:5], v[4:5], 0, s[34:35]
	global_load_dwordx4 v[18:21], v[4:5], off nt
	v_lshl_add_u64 v[4:5], v[4:5], 0, s[34:35]
	global_load_dwordx4 v[22:25], v[4:5], off nt
	v_lshl_add_u64 v[4:5], v[4:5], 0, s[34:35]
	global_load_dwordx4 v[26:29], v[4:5], off nt
	v_lshl_add_u64 v[4:5], v[4:5], 0, s[34:35]
	global_load_dwordx4 v[30:33], v[4:5], off nt
	v_lshl_add_u64 v[4:5], v[4:5], 0, s[34:35]
	global_load_dwordx4 v[34:37], v[4:5], off nt
	v_lshl_add_u64 v[4:5], v[4:5], 0, s[34:35]
	global_load_dwordx4 v[42:45], v[4:5], off nt
	v_lshl_add_u64 v[4:5], v[4:5], 0, s[34:35]
	global_load_dwordx4 v[46:49], v[4:5], off nt
	v_lshl_add_u64 v[4:5], v[4:5], 0, s[34:35]
	v_lshl_add_u64 v[2:3], v[12:13], 0, s[16:17]
	s_waitcnt vmcnt(7)
	v_cvt_pk_bf16_f32 v14, v14, v15
	v_cvt_pk_bf16_f32 v15, v16, v17
	global_store_dwordx2 v[6:7], v[14:15], off
	v_lshl_add_u64 v[6:7], v[6:7], 0, s[36:37]
	s_waitcnt vmcnt(7)
	v_cvt_pk_bf16_f32 v18, v18, v19
	v_cvt_pk_bf16_f32 v19, v20, v21
	global_store_dwordx2 v[6:7], v[18:19], off
	v_lshl_add_u64 v[6:7], v[6:7], 0, s[36:37]
	s_waitcnt vmcnt(7)
	v_cvt_pk_bf16_f32 v22, v22, v23
	v_cvt_pk_bf16_f32 v23, v24, v25
	global_store_dwordx2 v[6:7], v[22:23], off
	v_lshl_add_u64 v[6:7], v[6:7], 0, s[36:37]
	s_waitcnt vmcnt(7)
	v_cvt_pk_bf16_f32 v26, v26, v27
	v_cvt_pk_bf16_f32 v27, v28, v29
	global_store_dwordx2 v[6:7], v[26:27], off
	v_lshl_add_u64 v[6:7], v[6:7], 0, s[36:37]
	s_waitcnt vmcnt(7)
	v_cvt_pk_bf16_f32 v30, v30, v31
	v_cvt_pk_bf16_f32 v31, v32, v33
	global_store_dwordx2 v[6:7], v[30:31], off
	v_lshl_add_u64 v[6:7], v[6:7], 0, s[36:37]
	s_waitcnt vmcnt(7)
	v_cvt_pk_bf16_f32 v34, v34, v35
	v_cvt_pk_bf16_f32 v35, v36, v37
	global_store_dwordx2 v[6:7], v[34:35], off
	v_lshl_add_u64 v[6:7], v[6:7], 0, s[36:37]
	s_waitcnt vmcnt(7)
	v_cvt_pk_bf16_f32 v42, v42, v43
	v_cvt_pk_bf16_f32 v43, v44, v45
	global_store_dwordx2 v[6:7], v[42:43], off
	v_lshl_add_u64 v[6:7], v[6:7], 0, s[36:37]
	s_waitcnt vmcnt(7)
	v_cvt_pk_bf16_f32 v46, v46, v47
	v_cvt_pk_bf16_f32 v47, v48, v49
	global_store_dwordx2 v[6:7], v[46:47], off
	v_lshl_add_u64 v[6:7], v[6:7], 0, s[36:37]
	v_cmp_lt_u64_e32 vcc, s[40:41], v[2:3]
	s_or_b64 s[6:7], vcc, s[6:7]
	s_andn2_b64 exec, exec, s[6:7]
	s_cbranch_execz .LBB0_356
	s_branch .Lconvp8_a

.Lconvp8_b:
	v_lshl_add_u64 v[12:13], v[2:3], 0, s[88:89]
	v_lshl_add_u64 v[12:13], v[12:13], 0, s[88:89]
	v_lshl_add_u64 v[12:13], v[12:13], 0, s[88:89]
	v_lshl_add_u64 v[12:13], v[12:13], 0, s[88:89]
	v_lshl_add_u64 v[12:13], v[12:13], 0, s[88:89]
	v_lshl_add_u64 v[12:13], v[12:13], 0, s[88:89]
	v_lshl_add_u64 v[12:13], v[12:13], 0, s[88:89]
	v_cmp_lt_u64_e32 vcc, s[16:17], v[12:13]
	s_cbranch_vccnz .LBB0_1692
	global_load_dwordx4 v[14:17], v[4:5], off nt
	v_lshl_add_u64 v[4:5], v[4:5], 0, s[96:97]
	global_load_dwordx4 v[18:21], v[4:5], off nt
	v_lshl_add_u64 v[4:5], v[4:5], 0, s[96:97]
	global_load_dwordx4 v[22:25], v[4:5], off nt
	v_lshl_add_u64 v[4:5], v[4:5], 0, s[96:97]
	global_load_dwordx4 v[26:29], v[4:5], off nt
	v_lshl_add_u64 v[4:5], v[4:5], 0, s[96:97]
	global_load_dwordx4 v[30:33], v[4:5], off nt
	v_lshl_add_u64 v[4:5], v[4:5], 0, s[96:97]
	global_load_dwordx4 v[34:37], v[4:5], off nt
	v_lshl_add_u64 v[4:5], v[4:5], 0, s[96:97]
	global_load_dwordx4 v[42:45], v[4:5], off nt
	v_lshl_add_u64 v[4:5], v[4:5], 0, s[96:97]
	global_load_dwordx4 v[46:49], v[4:5], off nt
	v_lshl_add_u64 v[4:5], v[4:5], 0, s[96:97]
	v_lshl_add_u64 v[2:3], v[12:13], 0, s[88:89]
	s_waitcnt vmcnt(7)
	v_cvt_pk_bf16_f32 v14, v14, v15
	v_cvt_pk_bf16_f32 v15, v16, v17
	global_store_dwordx2 v[6:7], v[14:15], off
	v_lshl_add_u64 v[6:7], v[6:7], 0, s[14:15]
	s_waitcnt vmcnt(7)
	v_cvt_pk_bf16_f32 v18, v18, v19
	v_cvt_pk_bf16_f32 v19, v20, v21
	global_store_dwordx2 v[6:7], v[18:19], off
	v_lshl_add_u64 v[6:7], v[6:7], 0, s[14:15]
	s_waitcnt vmcnt(7)
	v_cvt_pk_bf16_f32 v22, v22, v23
	v_cvt_pk_bf16_f32 v23, v24, v25
	global_store_dwordx2 v[6:7], v[22:23], off
	v_lshl_add_u64 v[6:7], v[6:7], 0, s[14:15]
	s_waitcnt vmcnt(7)
	v_cvt_pk_bf16_f32 v26, v26, v27
	v_cvt_pk_bf16_f32 v27, v28, v29
	global_store_dwordx2 v[6:7], v[26:27], off
	v_lshl_add_u64 v[6:7], v[6:7], 0, s[14:15]
	s_waitcnt vmcnt(7)
	v_cvt_pk_bf16_f32 v30, v30, v31
	v_cvt_pk_bf16_f32 v31, v32, v33
	global_store_dwordx2 v[6:7], v[30:31], off
	v_lshl_add_u64 v[6:7], v[6:7], 0, s[14:15]
	s_waitcnt vmcnt(7)
	v_cvt_pk_bf16_f32 v34, v34, v35
	v_cvt_pk_bf16_f32 v35, v36, v37
	global_store_dwordx2 v[6:7], v[34:35], off
	v_lshl_add_u64 v[6:7], v[6:7], 0, s[14:15]
	s_waitcnt vmcnt(7)
	v_cvt_pk_bf16_f32 v42, v42, v43
	v_cvt_pk_bf16_f32 v43, v44, v45
	global_store_dwordx2 v[6:7], v[42:43], off
	v_lshl_add_u64 v[6:7], v[6:7], 0, s[14:15]
	s_waitcnt vmcnt(7)
	v_cvt_pk_bf16_f32 v46, v46, v47
	v_cvt_pk_bf16_f32 v47, v48, v49
	global_store_dwordx2 v[6:7], v[46:47], off
	v_lshl_add_u64 v[6:7], v[6:7], 0, s[14:15]
	v_cmp_lt_u64_e32 vcc, s[16:17], v[2:3]
	s_or_b64 s[2:3], vcc, s[2:3]
	s_andn2_b64 exec, exec, s[2:3]
	s_cbranch_execz .LBB0_1693
	s_branch .Lconvp8_b

; __device__ __forceinline__ float bflo(unsigned u) { return __uint_as_float(u << 16); }
; __device__ __forceinline__ float bfhi(unsigned u) { return __uint_as_float(u & 0xffff0000u); }
; __device__ __forceinline__ float ssf(const ssq_t* p) { return (float)(*p) * (1.0f / 1048576.0f); }
; __global__ void __launch_bounds__(512, 2) hybrid_fwd(Args args) {
;     ...
;         for (int m = gw; m < M; m += NGW) {
;             const float r = rsqrtf(ssf(ssfin + m) * (1.0f / D) + EPS);
;             const u32x2* br = (const u32x2*)(HBALT + (size_t)m * D) + lane;
;             f32x4* orow = (f32x4*)(H + (size_t)m * D) + lane; const f32x4* gr = (const f32x4*)gain + lane;
; #pragma unroll
;             for (int j = 0; j < 4; ++j) { const u32x2 w = br[64 * j]; const f32x4 g = gr[64 * j]; f32x4 o; o[0] = bflo(w.x) * r * g[0]; o[1] = bfhi(w.x) * r * g[1]; o[2] = bflo(w.y) * r * g[2]; o[3] = bfhi(w.y) * r * g[3]; __builtin_nontemporal_store(o, orow + 64 * j); }
;         }
.LBB0_1927:
	v_readlane_b32 s0, v252, 19
	v_readlane_b32 s1, v252, 20
	v_readlane_b32 s12, v254, 11
	v_readlane_b32 s14, v254, 13
	v_readlane_b32 s16, v254, 21
	s_mov_b64 s[2:3], 0
	s_andn2_b64 vcc, exec, s[0:1]
	v_readlane_b32 s8, v254, 15
	v_readlane_b32 s13, v254, 12
	v_readlane_b32 s15, v254, 14
	v_readlane_b32 s17, v254, 22
	v_readlane_b32 s9, v254, 16
	s_cbranch_vccnz .LBB0_1930
	s_lshl_b64 s[0:1], s[2:3], 3
	v_readlane_b32 s4, v252, 0
	v_readlane_b32 s5, v252, 1
	s_add_u32 s0, s4, s0
	s_addc_u32 s1, s5, s1
	s_load_dwordx2 s[0:1], s[0:1], 0xb0
	v_and_b32_e32 v4, 63, v194
	v_mov_b32_e32 v1, 0
	v_lshlrev_b32_e32 v0, 4, v4
	s_load_dwordx2 s[4:5], s[4:5], 0xb8
	s_waitcnt lgkmcnt(0)
	v_lshl_add_u64 v[2:3], s[0:1], 0, v[0:1]
	v_readlane_b32 s0, v254, 6
	v_readlane_b32 s1, v254, 7
	s_add_u32 s0, s2, s0
	s_addc_u32 s1, s3, s1
	v_readlane_b32 s10, v252, 7
	v_readlane_b32 s11, v252, 8
	s_add_u32 s0, s10, s0
	s_addc_u32 s1, s11, s1
	s_add_u32 s0, s0, 0x10710000
	s_addc_u32 s1, s1, 0
	v_readlane_b32 s6, v254, 17
	v_readlane_b32 s7, v254, 18
	s_add_u32 s6, s2, s6
	s_addc_u32 s7, s3, s7
	s_add_u32 s6, s10, s6
	s_addc_u32 s7, s11, s7
	s_lshl_b64 s[2:3], s[2:3], 2
	s_add_u32 s2, s4, s2
	s_addc_u32 s3, s5, s3
	v_readlane_b32 s4, v254, 52
	v_readlane_b32 s5, v254, 53
	s_add_u32 s2, s2, s4
	v_lshlrev_b32_e32 v4, 3, v4
	v_mov_b32_e32 v5, v1
	s_addc_u32 s3, s3, s5
	v_lshl_add_u64 v[4:5], s[6:7], 0, v[4:5]
	s_mov_b64 s[6:7], 0xc500400
	v_lshl_add_u64 v[6:7], s[2:3], 0, v[0:1]
	s_mov_b64 s[2:3], 0x800
	v_lshl_add_u64 v[4:5], v[4:5], 0, s[6:7]
	v_lshl_add_u64 v[6:7], v[6:7], 0, s[2:3]
	v_mov_b32_e32 v0, 0x358637bd
	s_mov_b32 s2, 0x800000
	global_load_dwordx2 v[12:13], v1, s[0:1]
	global_load_dwordx2 v[14:15], v[4:5], off offset:-1024
	global_load_dwordx2 v[36:37], v[4:5], off offset:-512
	global_load_dwordx2 v[38:39], v[4:5], off
	global_load_dwordx2 v[40:41], v[4:5], off offset:512
	global_load_dwordx4 v[20:23], v[2:3], off
	global_load_dwordx4 v[24:27], v[2:3], off offset:1024
	global_load_dwordx4 v[28:31], v[2:3], off offset:2048
	global_load_dwordx4 v[32:35], v[2:3], off offset:3072
	s_waitcnt vmcnt(0)
.LBB0_1929:
	s_waitcnt vmcnt(4)
	v_mov_b32_e32 v42, v12
	v_mov_b32_e32 v43, v13
	v_mov_b32_e32 v44, v14
	v_mov_b32_e32 v45, v15
	v_mov_b32_e32 v46, v36
	v_mov_b32_e32 v47, v37
	v_mov_b32_e32 v48, v38
	v_mov_b32_e32 v49, v39
	v_mov_b32_e32 v50, v40
	v_mov_b32_e32 v51, v41
	s_add_i32 s8, s8, s80
	s_add_u32 s0, s0, s12
	s_addc_u32 s1, s1, s13
	v_lshl_add_u64 v[4:5], v[4:5], 0, s[16:17]
	s_cmpk_gt_i32 s8, 0x3fff
	s_cbranch_scc1 .Lfnorm_last
	global_load_dwordx2 v[12:13], v1, s[0:1]
	global_load_dwordx2 v[14:15], v[4:5], off offset:-1024
	global_load_dwordx2 v[36:37], v[4:5], off offset:-512
	global_load_dwordx2 v[38:39], v[4:5], off
	global_load_dwordx2 v[40:41], v[4:5], off offset:512
.Lfnorm_last:
	v_ffbh_u32_e32 v18, v43
	v_min_u32_e32 v18, 32, v18
	v_lshlrev_b64 v[42:43], v18, v[42:43]
	v_min_u32_e32 v42, 1, v42
	v_or_b32_e32 v42, v43, v42
	v_cvt_f32_u32_e32 v42, v42
	v_sub_u32_e32 v18, 32, v18
	v_ldexp_f32 v42, v42, v18
	v_mul_f32_e32 v42, 0x35800000, v42
	v_fmamk_f32 v42, v42, 0x3a800000, v0
	v_mul_f32_e32 v43, 0x4b800000, v42
	v_cmp_gt_f32_e32 vcc, s2, v42
	s_nop 1
	v_cndmask_b32_e32 v42, v42, v43, vcc
	v_rsq_f32_e32 v42, v42
	s_nop 0
	v_mul_f32_e32 v43, 0x45800000, v42
	v_cndmask_b32_e32 v42, v42, v43, vcc
	v_lshlrev_b32_e32 v16, 16, v44
	v_and_b32_e32 v17, 0xffff0000, v44
	v_lshlrev_b32_e32 v52, 16, v45
	v_and_b32_e32 v53, 0xffff0000, v45
	v_pk_mul_f32 v[16:17], v[42:43], v[16:17] op_sel_hi:[0,1]
	v_pk_mul_f32 v[52:53], v[42:43], v[52:53] op_sel_hi:[0,1]
	v_pk_mul_f32 v[56:57], v[20:21], v[16:17]
	v_pk_mul_f32 v[58:59], v[22:23], v[52:53]
	global_store_dwordx4 v[6:7], v[56:59], off offset:-2048 nt
	v_lshlrev_b32_e32 v16, 16, v46
	v_and_b32_e32 v17, 0xffff0000, v46
	v_lshlrev_b32_e32 v52, 16, v47
	v_and_b32_e32 v53, 0xffff0000, v47
	v_pk_mul_f32 v[16:17], v[42:43], v[16:17] op_sel_hi:[0,1]
	v_pk_mul_f32 v[52:53], v[42:43], v[52:53] op_sel_hi:[0,1]
	v_pk_mul_f32 v[60:61], v[24:25], v[16:17]
	v_pk_mul_f32 v[62:63], v[26:27], v[52:53]
	global_store_dwordx4 v[6:7], v[60:63], off offset:-1024 nt
	v_lshlrev_b32_e32 v16, 16, v48
	v_and_b32_e32 v17, 0xffff0000, v48
	v_lshlrev_b32_e32 v52, 16, v49
	v_and_b32_e32 v53, 0xffff0000, v49
	v_pk_mul_f32 v[16:17], v[42:43], v[16:17] op_sel_hi:[0,1]
	v_pk_mul_f32 v[52:53], v[42:43], v[52:53] op_sel_hi:[0,1]
	v_pk_mul_f32 v[64:65], v[28:29], v[16:17]
	v_pk_mul_f32 v[66:67], v[30:31], v[52:53]
	global_store_dwordx4 v[6:7], v[64:67], off nt
	v_lshlrev_b32_e32 v16, 16, v50
	v_and_b32_e32 v17, 0xffff0000, v50
	v_lshlrev_b32_e32 v52, 16, v51
	v_and_b32_e32 v53, 0xffff0000, v51
	v_pk_mul_f32 v[16:17], v[42:43], v[16:17] op_sel_hi:[0,1]
	v_pk_mul_f32 v[52:53], v[42:43], v[52:53] op_sel_hi:[0,1]
	v_pk_mul_f32 v[68:69], v[32:33], v[16:17]
	v_pk_mul_f32 v[70:71], v[34:35], v[52:53]
	global_store_dwordx4 v[6:7], v[68:71], off offset:1024 nt
	v_lshl_add_u64 v[6:7], v[6:7], 0, s[14:15]
	s_cbranch_scc0 .LBB0_1929
